# attention epilogue: 8 dwordx2 row stores per lane widened to 4 dwordx4 via v_permlane32_swap between lane halves
# speedup vs baseline: 1.0097x; 1.0042x over previous
.LBB0_427:
	ds_bpermute_b32 v32, v141, v38
	s_add_u32 s8, s58, s78
	s_addc_u32 s9, s59, s79
	s_ashr_i32 s7, s6, 31
	s_lshl_b64 s[6:7], s[6:7], 14
	s_waitcnt lgkmcnt(0)
	v_add_f32_e32 v36, v38, v32
	v_div_scale_f32 v32, s[10:11], v36, v36, 1.0
	v_rcp_f32_e32 v33, v32
	v_div_scale_f32 v34, vcc, 1.0, v36, 1.0
	s_add_u32 s6, s6, s67
	v_fma_f32 v35, -v32, v33, 1.0
	v_fmac_f32_e32 v33, v35, v33
	v_mul_f32_e32 v35, v34, v33
	v_fma_f32 v38, -v32, v35, v34
	v_fmac_f32_e32 v35, v38, v33
	v_fma_f32 v32, -v32, v35, v34
	v_div_fmas_f32 v32, v32, v33, v35
	s_addc_u32 s7, s7, 0
	v_div_fixup_f32 v42, v32, v36, 1.0
	v_add_u32_e32 v34, s13, v139
	v_mov_b64_e32 v[32:33], s[6:7]
	v_ashrrev_i32_e32 v38, 31, v34
	v_mad_u64_u32 v[34:35], s[6:7], v34, s1, v[32:33]
	v_mov_b32_e32 v32, v35
	v_mad_u64_u32 v[32:33], s[6:7], v38, s1, v[32:33]
	v_mad_u64_u32 v[38:39], s[6:7], v34, s68, 0
	v_mov_b32_e32 v40, v39
	v_mad_u64_u32 v[40:41], s[6:7], v32, s68, v[40:41]
	v_mov_b32_e32 v39, v40
	v_lshl_add_u64 v[38:39], v[38:39], 1, s[8:9]
	s_ashr_i32 s13, s12, 31
	v_lshl_add_u64 v[38:39], s[12:13], 1, v[38:39]
	v_mov_b32_e32 v141, v88
	v_lshl_add_u64 v[38:39], v[38:39], 0, v[140:141]
	s_cmp_gt_i32 s0, -1
	s_cselect_b64 s[6:7], -1, 0
	s_and_b64 s[8:9], s[6:7], s[4:5]
	v_mbcnt_lo_u32_b32 v40, -1, 0
	v_mbcnt_hi_u32_b32 v40, -1, v40
	v_and_b32_e32 v40, 32, v40
	v_lshrrev_b32_e32 v40, 2, v40
	v_mov_b32_e32 v41, 0
	v_lshl_add_u64 v[38:39], v[38:39], 0, v[40:41]
	v_mul_f32_e32 v0, v0, v42
	v_mul_f32_e32 v1, v1, v42
	v_mul_f32_e32 v2, v2, v42
	v_mul_f32_e32 v3, v3, v42
	v_mul_f32_e32 v4, v4, v42
	v_mul_f32_e32 v5, v5, v42
	v_mul_f32_e32 v6, v6, v42
	v_mul_f32_e32 v7, v7, v42
	v_cvt_pk_bf16_f32 v0, v0, v1
	v_cvt_pk_bf16_f32 v1, v2, v3
	v_cvt_pk_bf16_f32 v2, v4, v5
	v_cvt_pk_bf16_f32 v3, v6, v7
	s_nop 1
	v_permlane32_swap_b32 v0, v2
	v_permlane32_swap_b32 v1, v3
	global_store_dwordx4 v[38:39], v[0:3], off
	v_mul_f32_e32 v8, v8, v42
	v_mul_f32_e32 v9, v9, v42
	v_mul_f32_e32 v10, v10, v42
	v_mul_f32_e32 v11, v11, v42
	v_mul_f32_e32 v12, v12, v42
	v_mul_f32_e32 v13, v13, v42
	v_mul_f32_e32 v14, v14, v42
	v_mul_f32_e32 v15, v15, v42
	v_cvt_pk_bf16_f32 v8, v8, v9
	v_cvt_pk_bf16_f32 v9, v10, v11
	v_cvt_pk_bf16_f32 v10, v12, v13
	v_cvt_pk_bf16_f32 v11, v14, v15
	s_nop 1
	v_permlane32_swap_b32 v8, v10
	v_permlane32_swap_b32 v9, v11
	global_store_dwordx4 v[38:39], v[8:11], off offset:32
	v_mul_f32_e32 v16, v16, v42
	v_mul_f32_e32 v17, v17, v42
	v_mul_f32_e32 v18, v18, v42
	v_mul_f32_e32 v19, v19, v42
	v_mul_f32_e32 v20, v20, v42
	v_mul_f32_e32 v21, v21, v42
	v_mul_f32_e32 v22, v22, v42
	v_mul_f32_e32 v23, v23, v42
	v_cvt_pk_bf16_f32 v16, v16, v17
	v_cvt_pk_bf16_f32 v17, v18, v19
	v_cvt_pk_bf16_f32 v18, v20, v21
	v_cvt_pk_bf16_f32 v19, v22, v23
	s_nop 1
	v_permlane32_swap_b32 v16, v18
	v_permlane32_swap_b32 v17, v19
	global_store_dwordx4 v[38:39], v[16:19], off offset:64
	v_mul_f32_e32 v24, v24, v42
	v_mul_f32_e32 v25, v25, v42
	v_mul_f32_e32 v26, v26, v42
	v_mul_f32_e32 v27, v27, v42
	v_mul_f32_e32 v28, v28, v42
	v_mul_f32_e32 v29, v29, v42
	v_mul_f32_e32 v30, v30, v42
	v_mul_f32_e32 v31, v31, v42
	v_cvt_pk_bf16_f32 v24, v24, v25
	v_cvt_pk_bf16_f32 v25, v26, v27
	v_cvt_pk_bf16_f32 v26, v28, v29
	v_cvt_pk_bf16_f32 v27, v30, v31
	s_nop 1
	v_permlane32_swap_b32 v24, v26
	v_permlane32_swap_b32 v25, v27
	global_store_dwordx4 v[38:39], v[24:27], off offset:96
	s_and_saveexec_b64 s[6:7], s[8:9]
	s_cbranch_execz .LBB0_385
	v_log_f32_e32 v2, v36
	v_readlane_b32 s8, v255, 22
	v_readlane_b32 s9, v255, 23
	s_mov_b32 s1, s15
	v_add_f32_e32 v4, v37, v2
	v_mad_u64_u32 v[0:1], s[8:9], v34, 48, s[8:9]
	v_mov_b32_e32 v2, v1
	v_mad_u64_u32 v[2:3], s[8:9], v32, 48, v[2:3]
	v_mov_b32_e32 v1, v2
	v_lshl_add_u64 v[0:1], s[0:1], 2, v[0:1]
	global_store_dword v[0:1], v4, off
	s_branch .LBB0_385

.LBB0_1287:
	ds_bpermute_b32 v32, v141, v38
	s_add_u32 s10, s58, s74
	s_addc_u32 s11, s59, s75
	s_ashr_i32 s5, s4, 31
	s_lshl_b64 s[4:5], s[4:5], 14
	s_waitcnt lgkmcnt(0)
	v_add_f32_e32 v36, v38, v32
	v_div_scale_f32 v32, s[12:13], v36, v36, 1.0
	v_rcp_f32_e32 v33, v32
	v_div_scale_f32 v34, vcc, 1.0, v36, 1.0
	s_add_u32 s4, s4, s65
	v_fma_f32 v35, -v32, v33, 1.0
	v_fmac_f32_e32 v33, v35, v33
	v_mul_f32_e32 v35, v34, v33
	v_fma_f32 v38, -v32, v35, v34
	v_fmac_f32_e32 v35, v38, v33
	v_fma_f32 v32, -v32, v35, v34
	v_div_fmas_f32 v32, v32, v33, v35
	s_addc_u32 s5, s5, 0
	v_div_fixup_f32 v42, v32, v36, 1.0
	v_add_u32_e32 v34, s7, v139
	v_mov_b64_e32 v[32:33], s[4:5]
	v_ashrrev_i32_e32 v38, 31, v34
	v_mad_u64_u32 v[34:35], s[4:5], v34, s1, v[32:33]
	v_mov_b32_e32 v32, v35
	v_mad_u64_u32 v[32:33], s[4:5], v38, s1, v[32:33]
	v_mad_u64_u32 v[38:39], s[4:5], v34, s66, 0
	v_mov_b32_e32 v40, v39
	v_mad_u64_u32 v[40:41], s[4:5], v32, s66, v[40:41]
	v_mov_b32_e32 v39, v40
	v_lshl_add_u64 v[38:39], v[38:39], 1, s[10:11]
	s_ashr_i32 s7, s6, 31
	v_lshl_add_u64 v[38:39], s[6:7], 1, v[38:39]
	v_mov_b32_e32 v141, v88
	v_lshl_add_u64 v[38:39], v[38:39], 0, v[140:141]
	s_cmp_gt_i32 s0, -1
	s_cselect_b64 s[4:5], -1, 0
	s_and_b64 s[6:7], s[4:5], s[8:9]
	v_mbcnt_lo_u32_b32 v40, -1, 0
	v_mbcnt_hi_u32_b32 v40, -1, v40
	v_and_b32_e32 v40, 32, v40
	v_lshrrev_b32_e32 v40, 2, v40
	v_mov_b32_e32 v41, 0
	v_lshl_add_u64 v[38:39], v[38:39], 0, v[40:41]
	v_mul_f32_e32 v0, v0, v42
	v_mul_f32_e32 v1, v1, v42
	v_mul_f32_e32 v2, v2, v42
	v_mul_f32_e32 v3, v3, v42
	v_mul_f32_e32 v4, v4, v42
	v_mul_f32_e32 v5, v5, v42
	v_mul_f32_e32 v6, v6, v42
	v_mul_f32_e32 v7, v7, v42
	v_cvt_pk_bf16_f32 v0, v0, v1
	v_cvt_pk_bf16_f32 v1, v2, v3
	v_cvt_pk_bf16_f32 v2, v4, v5
	v_cvt_pk_bf16_f32 v3, v6, v7
	s_nop 1
	v_permlane32_swap_b32 v0, v2
	v_permlane32_swap_b32 v1, v3
	global_store_dwordx4 v[38:39], v[0:3], off
	v_mul_f32_e32 v8, v8, v42
	v_mul_f32_e32 v9, v9, v42
	v_mul_f32_e32 v10, v10, v42
	v_mul_f32_e32 v11, v11, v42
	v_mul_f32_e32 v12, v12, v42
	v_mul_f32_e32 v13, v13, v42
	v_mul_f32_e32 v14, v14, v42
	v_mul_f32_e32 v15, v15, v42
	v_cvt_pk_bf16_f32 v8, v8, v9
	v_cvt_pk_bf16_f32 v9, v10, v11
	v_cvt_pk_bf16_f32 v10, v12, v13
	v_cvt_pk_bf16_f32 v11, v14, v15
	s_nop 1
	v_permlane32_swap_b32 v8, v10
	v_permlane32_swap_b32 v9, v11
	global_store_dwordx4 v[38:39], v[8:11], off offset:32
	v_mul_f32_e32 v16, v16, v42
	v_mul_f32_e32 v17, v17, v42
	v_mul_f32_e32 v18, v18, v42
	v_mul_f32_e32 v19, v19, v42
	v_mul_f32_e32 v20, v20, v42
	v_mul_f32_e32 v21, v21, v42
	v_mul_f32_e32 v22, v22, v42
	v_mul_f32_e32 v23, v23, v42
	v_cvt_pk_bf16_f32 v16, v16, v17
	v_cvt_pk_bf16_f32 v17, v18, v19
	v_cvt_pk_bf16_f32 v18, v20, v21
	v_cvt_pk_bf16_f32 v19, v22, v23
	s_nop 1
	v_permlane32_swap_b32 v16, v18
	v_permlane32_swap_b32 v17, v19
	global_store_dwordx4 v[38:39], v[16:19], off offset:64
	v_mul_f32_e32 v24, v24, v42
	v_mul_f32_e32 v25, v25, v42
	v_mul_f32_e32 v26, v26, v42
	v_mul_f32_e32 v27, v27, v42
	v_mul_f32_e32 v28, v28, v42
	v_mul_f32_e32 v29, v29, v42
	v_mul_f32_e32 v30, v30, v42
	v_mul_f32_e32 v31, v31, v42
	v_cvt_pk_bf16_f32 v24, v24, v25
	v_cvt_pk_bf16_f32 v25, v26, v27
	v_cvt_pk_bf16_f32 v26, v28, v29
	v_cvt_pk_bf16_f32 v27, v30, v31
	s_nop 1
	v_permlane32_swap_b32 v24, v26
	v_permlane32_swap_b32 v25, v27
	global_store_dwordx4 v[38:39], v[24:27], off offset:96
	s_and_saveexec_b64 s[4:5], s[6:7]
	s_cbranch_execz .LBB0_1245
	v_log_f32_e32 v2, v36
	v_readlane_b32 s6, v255, 22
	v_readlane_b32 s7, v255, 23
	s_mov_b32 s1, s15
	v_add_f32_e32 v4, v37, v2
	v_mad_u64_u32 v[0:1], s[6:7], v34, 48, s[6:7]
	v_mov_b32_e32 v2, v1
	v_mad_u64_u32 v[2:3], s[6:7], v32, 48, v[2:3]
	v_mov_b32_e32 v1, v2
	v_lshl_add_u64 v[0:1], s[0:1], 2, v[0:1]
	global_store_dword v[0:1], v4, off
	s_branch .LBB0_1245

.LBB0_2147:
	ds_bpermute_b32 v32, v141, v38
	s_add_u32 s12, s58, s46
	s_addc_u32 s13, s59, s47
	s_ashr_i32 s5, s4, 31
	s_lshl_b64 s[4:5], s[4:5], 14
	s_waitcnt lgkmcnt(0)
	v_add_f32_e32 v36, v38, v32
	v_div_scale_f32 v32, s[14:15], v36, v36, 1.0
	v_rcp_f32_e32 v33, v32
	v_div_scale_f32 v34, vcc, 1.0, v36, 1.0
	s_add_u32 s4, s4, s65
	v_fma_f32 v35, -v32, v33, 1.0
	v_fmac_f32_e32 v33, v35, v33
	v_mul_f32_e32 v35, v34, v33
	v_fma_f32 v38, -v32, v35, v34
	v_fmac_f32_e32 v35, v38, v33
	v_fma_f32 v32, -v32, v35, v34
	v_div_fmas_f32 v32, v32, v33, v35
	s_addc_u32 s5, s5, 0
	v_div_fixup_f32 v42, v32, v36, 1.0
	v_add_u32_e32 v34, s7, v139
	v_mov_b64_e32 v[32:33], s[4:5]
	v_ashrrev_i32_e32 v38, 31, v34
	v_mad_u64_u32 v[34:35], s[4:5], v34, s1, v[32:33]
	v_mov_b32_e32 v32, v35
	v_mad_u64_u32 v[32:33], s[4:5], v38, s1, v[32:33]
	v_mad_u64_u32 v[38:39], s[4:5], v34, s66, 0
	v_mov_b32_e32 v40, v39
	v_mad_u64_u32 v[40:41], s[4:5], v32, s66, v[40:41]
	v_mov_b32_e32 v39, v40
	v_lshl_add_u64 v[38:39], v[38:39], 1, s[12:13]
	s_ashr_i32 s7, s6, 31
	v_lshl_add_u64 v[38:39], s[6:7], 1, v[38:39]
	v_mov_b32_e32 v141, v88
	v_lshl_add_u64 v[38:39], v[38:39], 0, v[140:141]
	s_cmp_gt_i32 s0, -1
	s_cselect_b64 s[4:5], -1, 0
	s_and_b64 s[6:7], s[4:5], s[10:11]
	v_mbcnt_lo_u32_b32 v40, -1, 0
	v_mbcnt_hi_u32_b32 v40, -1, v40
	v_and_b32_e32 v40, 32, v40
	v_lshrrev_b32_e32 v40, 2, v40
	v_mov_b32_e32 v41, 0
	v_lshl_add_u64 v[38:39], v[38:39], 0, v[40:41]
	v_mul_f32_e32 v0, v0, v42
	v_mul_f32_e32 v1, v1, v42
	v_mul_f32_e32 v2, v2, v42
	v_mul_f32_e32 v3, v3, v42
	v_mul_f32_e32 v4, v4, v42
	v_mul_f32_e32 v5, v5, v42
	v_mul_f32_e32 v6, v6, v42
	v_mul_f32_e32 v7, v7, v42
	v_cvt_pk_bf16_f32 v0, v0, v1
	v_cvt_pk_bf16_f32 v1, v2, v3
	v_cvt_pk_bf16_f32 v2, v4, v5
	v_cvt_pk_bf16_f32 v3, v6, v7
	s_nop 1
	v_permlane32_swap_b32 v0, v2
	v_permlane32_swap_b32 v1, v3
	global_store_dwordx4 v[38:39], v[0:3], off
	v_mul_f32_e32 v8, v8, v42
	v_mul_f32_e32 v9, v9, v42
	v_mul_f32_e32 v10, v10, v42
	v_mul_f32_e32 v11, v11, v42
	v_mul_f32_e32 v12, v12, v42
	v_mul_f32_e32 v13, v13, v42
	v_mul_f32_e32 v14, v14, v42
	v_mul_f32_e32 v15, v15, v42
	v_cvt_pk_bf16_f32 v8, v8, v9
	v_cvt_pk_bf16_f32 v9, v10, v11
	v_cvt_pk_bf16_f32 v10, v12, v13
	v_cvt_pk_bf16_f32 v11, v14, v15
	s_nop 1
	v_permlane32_swap_b32 v8, v10
	v_permlane32_swap_b32 v9, v11
	global_store_dwordx4 v[38:39], v[8:11], off offset:32
	v_mul_f32_e32 v16, v16, v42
	v_mul_f32_e32 v17, v17, v42
	v_mul_f32_e32 v18, v18, v42
	v_mul_f32_e32 v19, v19, v42
	v_mul_f32_e32 v20, v20, v42
	v_mul_f32_e32 v21, v21, v42
	v_mul_f32_e32 v22, v22, v42
	v_mul_f32_e32 v23, v23, v42
	v_cvt_pk_bf16_f32 v16, v16, v17
	v_cvt_pk_bf16_f32 v17, v18, v19
	v_cvt_pk_bf16_f32 v18, v20, v21
	v_cvt_pk_bf16_f32 v19, v22, v23
	s_nop 1
	v_permlane32_swap_b32 v16, v18
	v_permlane32_swap_b32 v17, v19
	global_store_dwordx4 v[38:39], v[16:19], off offset:64
	v_mul_f32_e32 v24, v24, v42
	v_mul_f32_e32 v25, v25, v42
	v_mul_f32_e32 v26, v26, v42
	v_mul_f32_e32 v27, v27, v42
	v_mul_f32_e32 v28, v28, v42
	v_mul_f32_e32 v29, v29, v42
	v_mul_f32_e32 v30, v30, v42
	v_mul_f32_e32 v31, v31, v42
	v_cvt_pk_bf16_f32 v24, v24, v25
	v_cvt_pk_bf16_f32 v25, v26, v27
	v_cvt_pk_bf16_f32 v26, v28, v29
	v_cvt_pk_bf16_f32 v27, v30, v31
	s_nop 1
	v_permlane32_swap_b32 v24, v26
	v_permlane32_swap_b32 v25, v27
	global_store_dwordx4 v[38:39], v[24:27], off offset:96
	s_and_saveexec_b64 s[4:5], s[6:7]
	s_cbranch_execz .LBB0_2105
	v_log_f32_e32 v2, v36
	v_readlane_b32 s6, v255, 22
	v_readlane_b32 s7, v255, 23
	s_mov_b32 s1, s9
	v_add_f32_e32 v4, v37, v2
	v_mad_u64_u32 v[0:1], s[6:7], v34, 48, s[6:7]
	v_mov_b32_e32 v2, v1
	v_mad_u64_u32 v[2:3], s[6:7], v32, 48, v[2:3]
	v_mov_b32_e32 v1, v2
	v_lshl_add_u64 v[0:1], s[0:1], 2, v[0:1]
	global_store_dword v[0:1], v4, off
	s_branch .LBB0_2105

.LBB0_3011:
	ds_bpermute_b32 v32, v141, v38
	s_add_u32 s10, s58, s46
	s_addc_u32 s11, s59, s47
	s_ashr_i32 s5, s4, 31
	s_lshl_b64 s[4:5], s[4:5], 14
	s_waitcnt lgkmcnt(0)
	v_add_f32_e32 v36, v38, v32
	v_div_scale_f32 v32, s[12:13], v36, v36, 1.0
	v_rcp_f32_e32 v33, v32
	v_div_scale_f32 v34, vcc, 1.0, v36, 1.0
	s_add_u32 s4, s4, s53
	v_fma_f32 v35, -v32, v33, 1.0
	v_fmac_f32_e32 v33, v35, v33
	v_mul_f32_e32 v35, v34, v33
	v_fma_f32 v38, -v32, v35, v34
	v_fmac_f32_e32 v35, v38, v33
	v_fma_f32 v32, -v32, v35, v34
	v_div_fmas_f32 v32, v32, v33, v35
	s_addc_u32 s5, s5, 0
	v_div_fixup_f32 v42, v32, v36, 1.0
	v_add_u32_e32 v34, s9, v139
	v_mov_b64_e32 v[32:33], s[4:5]
	v_ashrrev_i32_e32 v38, 31, v34
	v_mad_u64_u32 v[34:35], s[4:5], v34, s1, v[32:33]
	v_mov_b32_e32 v32, v35
	v_mad_u64_u32 v[32:33], s[4:5], v38, s1, v[32:33]
	v_mad_u64_u32 v[38:39], s[4:5], v34, s54, 0
	v_mov_b32_e32 v40, v39
	v_mad_u64_u32 v[40:41], s[4:5], v32, s54, v[40:41]
	v_mov_b32_e32 v39, v40
	v_lshl_add_u64 v[38:39], v[38:39], 1, s[10:11]
	s_ashr_i32 s9, s8, 31
	v_lshl_add_u64 v[38:39], s[8:9], 1, v[38:39]
	v_mov_b32_e32 v141, v88
	v_lshl_add_u64 v[38:39], v[38:39], 0, v[140:141]
	s_cmp_gt_i32 s0, -1
	s_cselect_b64 s[4:5], -1, 0
	s_and_b64 s[8:9], s[4:5], s[6:7]
	v_mbcnt_lo_u32_b32 v40, -1, 0
	v_mbcnt_hi_u32_b32 v40, -1, v40
	v_and_b32_e32 v40, 32, v40
	v_lshrrev_b32_e32 v40, 2, v40
	v_mov_b32_e32 v41, 0
	v_lshl_add_u64 v[38:39], v[38:39], 0, v[40:41]
	v_mul_f32_e32 v0, v0, v42
	v_mul_f32_e32 v1, v1, v42
	v_mul_f32_e32 v2, v2, v42
	v_mul_f32_e32 v3, v3, v42
	v_mul_f32_e32 v4, v4, v42
	v_mul_f32_e32 v5, v5, v42
	v_mul_f32_e32 v6, v6, v42
	v_mul_f32_e32 v7, v7, v42
	v_cvt_pk_bf16_f32 v0, v0, v1
	v_cvt_pk_bf16_f32 v1, v2, v3
	v_cvt_pk_bf16_f32 v2, v4, v5
	v_cvt_pk_bf16_f32 v3, v6, v7
	s_nop 1
	v_permlane32_swap_b32 v0, v2
	v_permlane32_swap_b32 v1, v3
	global_store_dwordx4 v[38:39], v[0:3], off
	v_mul_f32_e32 v8, v8, v42
	v_mul_f32_e32 v9, v9, v42
	v_mul_f32_e32 v10, v10, v42
	v_mul_f32_e32 v11, v11, v42
	v_mul_f32_e32 v12, v12, v42
	v_mul_f32_e32 v13, v13, v42
	v_mul_f32_e32 v14, v14, v42
	v_mul_f32_e32 v15, v15, v42
	v_cvt_pk_bf16_f32 v8, v8, v9
	v_cvt_pk_bf16_f32 v9, v10, v11
	v_cvt_pk_bf16_f32 v10, v12, v13
	v_cvt_pk_bf16_f32 v11, v14, v15
	s_nop 1
	v_permlane32_swap_b32 v8, v10
	v_permlane32_swap_b32 v9, v11
	global_store_dwordx4 v[38:39], v[8:11], off offset:32
	v_mul_f32_e32 v16, v16, v42
	v_mul_f32_e32 v17, v17, v42
	v_mul_f32_e32 v18, v18, v42
	v_mul_f32_e32 v19, v19, v42
	v_mul_f32_e32 v20, v20, v42
	v_mul_f32_e32 v21, v21, v42
	v_mul_f32_e32 v22, v22, v42
	v_mul_f32_e32 v23, v23, v42
	v_cvt_pk_bf16_f32 v16, v16, v17
	v_cvt_pk_bf16_f32 v17, v18, v19
	v_cvt_pk_bf16_f32 v18, v20, v21
	v_cvt_pk_bf16_f32 v19, v22, v23
	s_nop 1
	v_permlane32_swap_b32 v16, v18
	v_permlane32_swap_b32 v17, v19
	global_store_dwordx4 v[38:39], v[16:19], off offset:64
	v_mul_f32_e32 v24, v24, v42
	v_mul_f32_e32 v25, v25, v42
	v_mul_f32_e32 v26, v26, v42
	v_mul_f32_e32 v27, v27, v42
	v_mul_f32_e32 v28, v28, v42
	v_mul_f32_e32 v29, v29, v42
	v_mul_f32_e32 v30, v30, v42
	v_mul_f32_e32 v31, v31, v42
	v_cvt_pk_bf16_f32 v24, v24, v25
	v_cvt_pk_bf16_f32 v25, v26, v27
	v_cvt_pk_bf16_f32 v26, v28, v29
	v_cvt_pk_bf16_f32 v27, v30, v31
	s_nop 1
	v_permlane32_swap_b32 v24, v26
	v_permlane32_swap_b32 v25, v27
	global_store_dwordx4 v[38:39], v[24:27], off offset:96
	s_and_saveexec_b64 s[4:5], s[8:9]
	s_cbranch_execz .LBB0_2969
	v_log_f32_e32 v2, v36
	v_readlane_b32 s8, v255, 22
	v_readlane_b32 s9, v255, 23
	s_mov_b32 s1, s17
	v_add_f32_e32 v4, v37, v2
	v_mad_u64_u32 v[0:1], s[8:9], v34, 48, s[8:9]
	v_mov_b32_e32 v2, v1
	v_mad_u64_u32 v[2:3], s[8:9], v32, 48, v[2:3]
	v_mov_b32_e32 v1, v2
	v_lshl_add_u64 v[0:1], s[0:1], 2, v[0:1]
	global_store_dword v[0:1], v4, off
	s_branch .LBB0_2969
